# final RMSNorm loop rewritten by hand: gains hoisted, rows double-buffered, DPP reduction
# baseline (speedup 1.0000x reference)
; __device__ __forceinline__ void rms_row_final(float* xrow, const float* g, int lane) {
;     f32x4* xr = (f32x4*)xrow + lane; const f32x4* gr = (const f32x4*)g + lane; f32x4 v[4]; float s = 0.f;
; #pragma unroll
;     for (int j = 0; j < 4; ++j) { v[j] = xr[64 * j]; s += (v[j].x * v[j].x + v[j].y * v[j].y) + (v[j].z * v[j].z + v[j].w * v[j].w); }
;     const float rstd = rsqrtf(wave_sum(s) * (1.0f / DM) + EPSN);
; #pragma unroll
;     for (int j = 0; j < 4; ++j) xr[64 * j] = v[j] * rstd * gr[64 * j];
; }
; __global__ void __launch_bounds__(512) fwd_megakernel(Args a) {
;     ...
;     for (int m = gw, it_ = 0; it_ < T / 2048; ++it_, m += 2048) rms_row_final(out + (size_t)m * DM, ap->in[4], lane);
.LBB0_1375:
	s_load_dwordx2 s[0:1], s[6:7], 0x20
	s_load_dwordx2 s[2:3], s[6:7], 0xa0
	v_ashrrev_i32_e32 v1, 31, v0
	v_lshlrev_b64 v[2:3], 4, v[0:1]
	v_mov_b32_e32 v4, 0x358637bd
	s_waitcnt lgkmcnt(0)
	v_lshl_add_u64 v[0:1], s[0:1], 0, v[2:3]
	v_readlane_b32 s0, v254, 7
	v_readlane_b32 s1, v254, 8
	s_add_u32 s0, s2, s0
	s_addc_u32 s1, s3, s1
	v_lshl_add_u64 v[2:3], s[0:1], 0, v[2:3]
	s_mov_b64 s[0:1], 0
	s_mov_b32 s2, 0x800000
	s_mov_b32 s4, 0x800000
	s_mov_b32 s5, 0
	global_load_dwordx4 v[6:9], v[2:3], off
	global_load_dwordx4 v[10:13], v[2:3], off offset:1024
	global_load_dwordx4 v[14:17], v[2:3], off offset:2048
	global_load_dwordx4 v[18:21], v[2:3], off offset:3072
	global_load_dwordx4 v[44:47], v[0:1], off
	global_load_dwordx4 v[48:51], v[0:1], off offset:1024
	global_load_dwordx4 v[52:55], v[0:1], off offset:2048
	global_load_dwordx4 v[56:59], v[0:1], off offset:3072
	v_lshl_add_u64 v[26:27], v[2:3], 0, s[4:5]
	global_load_dwordx4 v[60:63], v[26:27], off
	global_load_dwordx4 v[64:67], v[26:27], off offset:1024
	global_load_dwordx4 v[68:71], v[26:27], off offset:2048
	global_load_dwordx4 v[72:75], v[26:27], off offset:3072
	s_mov_b32 s0, 0
	s_waitcnt vmcnt(4)
	s_branch .Lfn_procA
.Lfn_loop:
	v_lshl_add_u64 v[26:27], v[2:3], 0, s[4:5]
	global_load_dwordx4 v[60:63], v[26:27], off
	global_load_dwordx4 v[64:67], v[26:27], off offset:1024
	global_load_dwordx4 v[68:71], v[26:27], off offset:2048
	global_load_dwordx4 v[72:75], v[26:27], off offset:3072
	s_waitcnt vmcnt(8)
.Lfn_procA:
	v_pk_mul_f32 v[30:31], v[6:7], v[6:7]
	v_pk_fma_f32 v[30:31], v[8:9], v[8:9], v[30:31]
	v_pk_fma_f32 v[30:31], v[10:11], v[10:11], v[30:31]
	v_pk_fma_f32 v[30:31], v[12:13], v[12:13], v[30:31]
	v_pk_fma_f32 v[30:31], v[14:15], v[14:15], v[30:31]
	v_pk_fma_f32 v[30:31], v[16:17], v[16:17], v[30:31]
	v_pk_fma_f32 v[30:31], v[18:19], v[18:19], v[30:31]
	v_pk_fma_f32 v[30:31], v[20:21], v[20:21], v[30:31]
	v_add_f32_e32 v5, v30, v31
	s_nop 1
	v_add_f32_dpp v5, v5, v5 quad_perm:[1,0,3,2] row_mask:0xf bank_mask:0xf
	s_nop 1
	v_add_f32_dpp v5, v5, v5 quad_perm:[2,3,0,1] row_mask:0xf bank_mask:0xf
	s_nop 1
	v_add_f32_dpp v5, v5, v5 row_half_mirror row_mask:0xf bank_mask:0xf
	s_nop 1
	v_add_f32_dpp v5, v5, v5 row_mirror row_mask:0xf bank_mask:0xf
	s_nop 0
	v_readlane_b32 s8, v5, 0
	v_readlane_b32 s9, v5, 16
	v_readlane_b32 s10, v5, 32
	v_readlane_b32 s11, v5, 48
	v_mov_b32_e32 v28, s8
	v_add_f32_e32 v28, s9, v28
	v_add_f32_e32 v28, s10, v28
	v_add_f32_e32 v28, s11, v28
	v_fmamk_f32 v28, v28, 0x3a800000, v4
	v_rsq_f32_e32 v28, v28
	s_nop 0
	v_pk_mul_f32 v[6:7], v[6:7], v[28:29] op_sel_hi:[1,0]
	v_pk_mul_f32 v[8:9], v[8:9], v[28:29] op_sel_hi:[1,0]
	v_pk_mul_f32 v[10:11], v[10:11], v[28:29] op_sel_hi:[1,0]
	v_pk_mul_f32 v[12:13], v[12:13], v[28:29] op_sel_hi:[1,0]
	v_pk_mul_f32 v[14:15], v[14:15], v[28:29] op_sel_hi:[1,0]
	v_pk_mul_f32 v[16:17], v[16:17], v[28:29] op_sel_hi:[1,0]
	v_pk_mul_f32 v[18:19], v[18:19], v[28:29] op_sel_hi:[1,0]
	v_pk_mul_f32 v[20:21], v[20:21], v[28:29] op_sel_hi:[1,0]
	v_pk_mul_f32 v[6:7], v[44:45], v[6:7]
	v_pk_mul_f32 v[8:9], v[46:47], v[8:9]
	v_pk_mul_f32 v[10:11], v[48:49], v[10:11]
	v_pk_mul_f32 v[12:13], v[50:51], v[12:13]
	v_pk_mul_f32 v[14:15], v[52:53], v[14:15]
	v_pk_mul_f32 v[16:17], v[54:55], v[16:17]
	v_pk_mul_f32 v[18:19], v[56:57], v[18:19]
	v_pk_mul_f32 v[20:21], v[58:59], v[20:21]
	global_store_dwordx4 v[2:3], v[6:9], off
	global_store_dwordx4 v[2:3], v[10:13], off offset:1024
	global_store_dwordx4 v[2:3], v[14:17], off offset:2048
	global_store_dwordx4 v[2:3], v[18:21], off offset:3072
	s_cmp_eq_u32 s0, 11
	s_cbranch_scc1 .Lfn_lastB
	v_lshl_add_u64 v[2:3], v[26:27], 0, s[4:5]
	global_load_dwordx4 v[6:9], v[2:3], off
	global_load_dwordx4 v[10:13], v[2:3], off offset:1024
	global_load_dwordx4 v[14:17], v[2:3], off offset:2048
	global_load_dwordx4 v[18:21], v[2:3], off offset:3072
	s_waitcnt vmcnt(8)
	s_branch .Lfn_procB

; __device__ __forceinline__ void rms_row_final(float* xrow, const float* g, int lane) {
;     f32x4* xr = (f32x4*)xrow + lane; const f32x4* gr = (const f32x4*)g + lane; f32x4 v[4]; float s = 0.f;
; #pragma unroll
;     for (int j = 0; j < 4; ++j) { v[j] = xr[64 * j]; s += (v[j].x * v[j].x + v[j].y * v[j].y) + (v[j].z * v[j].z + v[j].w * v[j].w); }
;     const float rstd = rsqrtf(wave_sum(s) * (1.0f / DM) + EPSN);
; #pragma unroll
;     for (int j = 0; j < 4; ++j) xr[64 * j] = v[j] * rstd * gr[64 * j];
; }
; __global__ void __launch_bounds__(512) fwd_megakernel(Args a) {
;     ...
;     for (int m = gw, it_ = 0; it_ < T / 2048; ++it_, m += 2048) rms_row_final(out + (size_t)m * DM, ap->in[4], lane);
.Lfn_procB:
	v_pk_mul_f32 v[30:31], v[60:61], v[60:61]
	v_pk_fma_f32 v[30:31], v[62:63], v[62:63], v[30:31]
	v_pk_fma_f32 v[30:31], v[64:65], v[64:65], v[30:31]
	v_pk_fma_f32 v[30:31], v[66:67], v[66:67], v[30:31]
	v_pk_fma_f32 v[30:31], v[68:69], v[68:69], v[30:31]
	v_pk_fma_f32 v[30:31], v[70:71], v[70:71], v[30:31]
	v_pk_fma_f32 v[30:31], v[72:73], v[72:73], v[30:31]
	v_pk_fma_f32 v[30:31], v[74:75], v[74:75], v[30:31]
	v_add_f32_e32 v5, v30, v31
	s_nop 1
	v_add_f32_dpp v5, v5, v5 quad_perm:[1,0,3,2] row_mask:0xf bank_mask:0xf
	s_nop 1
	v_add_f32_dpp v5, v5, v5 quad_perm:[2,3,0,1] row_mask:0xf bank_mask:0xf
	s_nop 1
	v_add_f32_dpp v5, v5, v5 row_half_mirror row_mask:0xf bank_mask:0xf
	s_nop 1
	v_add_f32_dpp v5, v5, v5 row_mirror row_mask:0xf bank_mask:0xf
	s_nop 0
	v_readlane_b32 s8, v5, 0
	v_readlane_b32 s9, v5, 16
	v_readlane_b32 s10, v5, 32
	v_readlane_b32 s11, v5, 48
	v_mov_b32_e32 v28, s8
	v_add_f32_e32 v28, s9, v28
	v_add_f32_e32 v28, s10, v28
	v_add_f32_e32 v28, s11, v28
	v_fmamk_f32 v28, v28, 0x3a800000, v4
	v_rsq_f32_e32 v28, v28
	s_nop 0
	v_pk_mul_f32 v[60:61], v[60:61], v[28:29] op_sel_hi:[1,0]
	v_pk_mul_f32 v[62:63], v[62:63], v[28:29] op_sel_hi:[1,0]
	v_pk_mul_f32 v[64:65], v[64:65], v[28:29] op_sel_hi:[1,0]
	v_pk_mul_f32 v[66:67], v[66:67], v[28:29] op_sel_hi:[1,0]
	v_pk_mul_f32 v[68:69], v[68:69], v[28:29] op_sel_hi:[1,0]
	v_pk_mul_f32 v[70:71], v[70:71], v[28:29] op_sel_hi:[1,0]
	v_pk_mul_f32 v[72:73], v[72:73], v[28:29] op_sel_hi:[1,0]
	v_pk_mul_f32 v[74:75], v[74:75], v[28:29] op_sel_hi:[1,0]
	v_pk_mul_f32 v[60:61], v[44:45], v[60:61]
	v_pk_mul_f32 v[62:63], v[46:47], v[62:63]
	v_pk_mul_f32 v[64:65], v[48:49], v[64:65]
	v_pk_mul_f32 v[66:67], v[50:51], v[66:67]
	v_pk_mul_f32 v[68:69], v[52:53], v[68:69]
	v_pk_mul_f32 v[70:71], v[54:55], v[70:71]
	v_pk_mul_f32 v[72:73], v[56:57], v[72:73]
	v_pk_mul_f32 v[74:75], v[58:59], v[74:75]
	global_store_dwordx4 v[26:27], v[60:63], off
	global_store_dwordx4 v[26:27], v[64:67], off offset:1024
	global_store_dwordx4 v[26:27], v[68:71], off offset:2048
	global_store_dwordx4 v[26:27], v[72:75], off offset:3072
	s_add_i32 s0, s0, 1
	s_cmp_lt_u32 s0, 12
	s_cbranch_scc1 .Lfn_loop
	s_endpgm
